# mlstmA: gate chains of all 16 items precomputed by the 8 waves in parallel (per-item win slots in LDS), gate block removed from the item loop
# speedup vs baseline: 1.0090x; 1.0004x over previous
; DI int otid() { int t = __builtin_amdgcn_workitem_id_x(); asm volatile("" : "+v"(t)); return t; }
; DI void mlstmA_item(const Params& p, char* lds, int item) {
;   char* ws = p.ws;
;   const int bh = item >> 7, c = item & 127, b = bh >> 2, hd = bh & 3;
;   const int tid = otid(), lane = tid & 63, wave = tid >> 6, hh = lane >> 5, l31 = lane & 31;
;   u16* KTs = (u16*)lds;
;   u16* VTs = KTs + 128 * 72;
;   float* win = (float*)(VTs + 128 * 72);
;   const u16* PM = (const u16*)(ws + OFF_PM); const u16* VTm = (const u16*)(ws + OFF_VTM);
;   const float* G = (const float*)(ws + OFF_G);
;   u16* KVS = (u16*)(ws + OFF_KVS) + (size_t)item * 16384; float* KSUM = (float*)(ws + OFF_KSUM) + (size_t)item * 128; float* CSC = (float*)(ws + OFF_CSC) + (size_t)item * 4;
;   if (wave == 0) {
; DI void phase_mixA(const Params& p, char* lds) {
;   for (int it = blockIdx.x; it < 4096; it += gridDim.x) mlstmA_item(p, lds, it);
.LBB0_321:
	s_or_b64 exec, exec, s[0:1]
	s_cmpk_gt_i32 s94, 0xfff
	s_waitcnt lgkmcnt(0)
	s_barrier
	s_cbranch_scc1 .LBB0_342
	s_add_u32 s4, s68, 0x16800000
	s_addc_u32 s5, s69, 0
	s_add_u32 s6, s68, 0x22800000
	s_addc_u32 s7, s69, 0
	s_add_u32 s2, s68, 0x32800000
	s_addc_u32 s16, s69, 0
	s_add_u32 s17, s68, 0x3a800000
	s_addc_u32 s20, s69, 0
	v_mbcnt_hi_u32_b32 v34, -1, v203
	s_add_u32 s21, s68, 0x3aa00000
	v_and_b32_e32 v35, 64, v34
	v_bfrev_b32_e32 v0, 0.5
	s_addc_u32 s22, s69, 0
	s_mov_b32 s9, 0
	s_mov_b32 s23, 0xbfb8aa3b
	v_mov_b32_e32 v32, 0x3ecc95a3
	v_mov_b32_e32 v17, 0
	s_movk_i32 s26, 0x90
	v_mov_b32_e32 v33, 0x7f800000
	v_add_u32_e32 v36, -1, v34
	v_add_u32_e32 v37, -2, v34
	v_add_u32_e32 v38, -4, v34
	v_add_u32_e32 v39, -8, v34
	v_add_u32_e32 v40, -16, v34
	v_subrev_u32_e32 v41, 32, v34
	v_add_u32_e32 v42, 64, v35
	v_xor_b32_e32 v43, 32, v34
	v_xor_b32_e32 v44, 16, v34
	v_xor_b32_e32 v45, 8, v34
	v_xor_b32_e32 v46, 4, v34
	v_xor_b32_e32 v47, 2, v34
	v_xor_b32_e32 v48, 1, v34
	v_lshl_or_b32 v49, v34, 2, v0
	s_mov_b32 s10, s94
	v_and_b32_e32 v19, 63, v222
	v_readfirstlane_b32 s81, v222
	s_nop 3
	s_lshr_b32 s81, s81, 6
	s_mov_b32 s80, 0
; DI float wmax(float v) { for (int o = 32; o; o >>= 1) v = fmaxf(v, __shfl_xor(v, o)); return v; }
; DI float scan_sum(float v, int lane) { for (int o = 1; o < 64; o <<= 1) { float tv = __shfl_up(v, o); if (lane >= o) v += tv; } return v; }
; DI float log_sigmoid(float f) { return fminf(f, 0.f) - log1pf(expf(-fabsf(f))); }
; DI void mlstmA_item(const Params& p, char* lds, int item) {
;     ...
;   if (wave == 0) {
;     const size_t row = (size_t)b * SEQ + c * 64 + lane;
;     const float ig = G[row * 8 + hd] + p.in[7][hd], fg = G[row * 8 + 4 + hd] + p.in[8][hd];
;     const float bc = scan_sum(log_sigmoid(fg), lane);
;     const float as = ig - bc;
;     const float gmax = wmax(as);
;     const float B = __shfl(bc, 63);
;     win[lane] = expf(as - gmax);
;     if (lane == 0) { CSC[0] = B; CSC[1] = B + gmax; }
;   }
.Lmg_round:
	s_lshl_b32 s32, s80, 3
	s_add_u32 s32, s32, s81
	s_mul_i32 s10, s32, s70
	s_add_i32 s10, s10, s94
	s_cmpk_gt_i32 s10, 0xfff
	s_cbranch_scc1 .Lmg_next
	s_lshl_b32 s32, s32, 8
	s_and_b32 s18, s10, 0x7f
	s_ashr_i32 s12, s10, 9
	s_bfe_u32 s27, s10, 0x20007
	s_ashr_i32 s11, s10, 31
	s_ashr_i32 s13, s12, 31
	s_lshl_b64 s[0:1], s[12:13], 13
	s_lshl_b32 s18, s18, 6
	v_or_b32_e32 v0, s0, v19
	v_or_b32_e32 v0, s18, v0
	v_mov_b32_e32 v1, s1
	v_lshlrev_b64 v[0:1], 5, v[0:1]
	v_lshl_add_u64 v[0:1], s[52:53], 0, v[0:1]
	s_lshl_b32 s8, s27, 2
	v_lshl_add_u64 v[2:3], v[0:1], 0, s[8:9]
	v_mov_b32_e32 v1, s8
	global_load_dword v0, v[2:3], off
	global_load_dword v4, v1, s[66:67]
	s_nop 0
	global_load_dword v2, v[2:3], off offset:16
	s_nop 0
	global_load_dword v1, v1, s[36:37]
	s_mov_b32 s0, 0xb2a5705f
	s_waitcnt vmcnt(2)
	v_add_f32_e32 v0, v0, v4
	s_waitcnt vmcnt(0)
	v_add_f32_e32 v1, v2, v1
	v_mul_f32_e64 v2, |v1|, s23
	v_fma_f32 v3, |v1|, s23, -v2
	v_rndne_f32_e32 v5, v2
	v_fma_f32 v3, |v1|, s0, v3
	v_sub_f32_e32 v2, v2, v5
	v_add_f32_e32 v2, v2, v3
	v_exp_f32_e32 v2, v2
	v_cvt_i32_f32_e32 v3, v5
	s_mov_b32 s0, 0x42ce8ed0
	v_cmp_ngt_f32_e64 vcc, |v1|, s0
	s_mov_b32 s0, 0xc2b17218
	v_ldexp_f32 v2, v2, v3
	v_cndmask_b32_e32 v2, 0, v2, vcc
	v_cmp_nlt_f32_e64 vcc, |v1|, s0
	v_min_f32_e32 v4, 0, v1
	s_mov_b32 s0, 0x3f2aaaab
	v_cndmask_b32_e32 v1, v33, v2, vcc
	v_add_f32_e32 v5, 1.0, v1
	v_add_f32_e32 v2, -1.0, v5
	v_sub_f32_e32 v3, v2, v5
	v_add_f32_e32 v3, 1.0, v3
	v_sub_f32_e32 v2, v1, v2
	v_add_f32_e32 v6, v2, v3
	v_frexp_mant_f32_e32 v2, v5
	v_cmp_gt_f32_e32 vcc, s0, v2
	v_cvt_f64_f32_e32 v[2:3], v5
	v_frexp_exp_i32_f64_e32 v2, v[2:3]
	v_subbrev_co_u32_e32 v2, vcc, 0, v2, vcc
	v_sub_u32_e32 v3, 0, v2
	v_ldexp_f32 v5, v5, v3
	v_ldexp_f32 v3, v6, v3
	v_add_f32_e32 v6, -1.0, v5
	v_add_f32_e32 v7, 1.0, v6
	v_sub_f32_e32 v7, v5, v7
	v_add_f32_e32 v7, v3, v7
	v_add_f32_e32 v8, v6, v7
	v_sub_f32_e32 v6, v6, v8
	v_add_f32_e32 v6, v7, v6
	v_add_f32_e32 v7, 1.0, v5
	v_add_f32_e32 v9, -1.0, v7
	v_sub_f32_e32 v5, v5, v9
	v_add_f32_e32 v3, v3, v5
	v_add_f32_e32 v5, v7, v3
	v_sub_f32_e32 v7, v7, v5
	v_add_f32_e32 v3, v3, v7
	v_rcp_f32_e32 v7, v5
	v_cvt_f32_i32_e32 v2, v2
	s_mov_b32 s0, 0x3f317218
	v_mul_f32_e32 v9, v8, v7
	v_mul_f32_e32 v10, v5, v9
	v_fma_f32 v11, v9, v5, -v10
	v_fmac_f32_e32 v11, v9, v3
	v_add_f32_e32 v12, v10, v11
	v_sub_f32_e32 v13, v8, v12
	v_sub_f32_e32 v8, v8, v13
	v_sub_f32_e32 v10, v12, v10
	v_sub_f32_e32 v8, v8, v12
	v_add_f32_e32 v6, v6, v8
	v_sub_f32_e32 v8, v10, v11
	v_add_f32_e32 v6, v8, v6
	v_add_f32_e32 v8, v13, v6
	v_mul_f32_e32 v10, v7, v8
	v_mul_f32_e32 v11, v5, v10
	v_fma_f32 v5, v10, v5, -v11
	v_fmac_f32_e32 v5, v10, v3
	v_sub_f32_e32 v3, v13, v8
	v_add_f32_e32 v3, v6, v3
	v_add_f32_e32 v6, v11, v5
	v_sub_f32_e32 v12, v8, v6
	v_sub_f32_e32 v8, v8, v12
	v_sub_f32_e32 v11, v6, v11
	v_sub_f32_e32 v6, v8, v6
	v_add_f32_e32 v3, v3, v6
	v_sub_f32_e32 v5, v11, v5
	v_add_f32_e32 v3, v5, v3
	v_add_f32_e32 v5, v9, v10
	v_add_f32_e32 v3, v12, v3
	v_sub_f32_e32 v6, v5, v9
	v_mul_f32_e32 v3, v7, v3
	v_sub_f32_e32 v6, v10, v6
	v_add_f32_e32 v3, v6, v3
	v_mul_f32_e32 v9, 0x3f317218, v2
	v_add_f32_e32 v6, v5, v3
	v_fma_f32 v10, v2, s0, -v9
	v_mul_f32_e32 v7, v6, v6
	v_fmac_f32_e32 v10, 0xb102e308, v2
	v_sub_f32_e32 v2, v6, v5
	v_fmamk_f32 v8, v7, 0x3e9b6dac, v32
	v_sub_f32_e32 v2, v3, v2
	v_add_f32_e32 v3, v9, v10
	v_fmaak_f32 v8, v7, v8, 0x3f2aaada
	v_sub_f32_e32 v5, v3, v9
	v_ldexp_f32 v9, v6, 1
	v_mul_f32_e32 v6, v6, v7
	v_mul_f32_e32 v6, v6, v8
	v_add_f32_e32 v7, v9, v6
	v_sub_f32_e32 v8, v7, v9
	v_ldexp_f32 v2, v2, 1
	v_sub_f32_e32 v6, v6, v8
	v_add_f32_e32 v2, v2, v6
	v_add_f32_e32 v6, v7, v2
	v_sub_f32_e32 v7, v6, v7
	v_sub_f32_e32 v2, v2, v7
	v_add_f32_e32 v7, v3, v6
	v_sub_f32_e32 v8, v7, v3
	v_sub_f32_e32 v9, v7, v8
	v_sub_f32_e32 v5, v10, v5
	v_sub_f32_e32 v3, v3, v9
	v_sub_f32_e32 v6, v6, v8
	v_add_f32_e32 v3, v6, v3
	v_add_f32_e32 v6, v5, v2
	v_sub_f32_e32 v8, v6, v5
	v_sub_f32_e32 v9, v6, v8
	v_sub_f32_e32 v5, v5, v9
	v_sub_f32_e32 v2, v2, v8
	v_add_f32_e32 v3, v6, v3
	v_add_f32_e32 v2, v2, v5
	v_add_f32_e32 v5, v7, v3
	v_sub_f32_e32 v6, v5, v7
	v_sub_f32_e32 v3, v3, v6
	v_add_f32_e32 v2, v2, v3
	s_mov_b32 s0, 0x7f800000
	v_add_f32_e32 v2, v5, v2
	v_cmp_neq_f32_e32 vcc, s0, v1
	s_mov_b32 s0, 0x33800000
	s_nop 0
	v_cndmask_b32_e32 v2, v33, v2, vcc
	v_cmp_lt_f32_e64 vcc, |v1|, s0
	s_nop 0
	v_cndmask_b32_e32 v1, v2, v1, vcc
	v_sub_f32_e32 v1, v4, v1
	s_nop 1
	v_add_f32_dpp v1, v1, v1 row_shr:1 row_mask:0xf bank_mask:0xf
	s_nop 1
	v_add_f32_dpp v1, v1, v1 row_shr:2 row_mask:0xf bank_mask:0xf
	s_nop 1
	v_add_f32_dpp v1, v1, v1 row_shr:4 row_mask:0xf bank_mask:0xf
	s_nop 1
	v_add_f32_dpp v1, v1, v1 row_shr:8 row_mask:0xf bank_mask:0xf
	s_nop 1
	v_add_f32_dpp v1, v1, v1 row_bcast:15 row_mask:0xa bank_mask:0xf
	s_nop 1
	v_add_f32_dpp v1, v1, v1 row_bcast:31 row_mask:0xc bank_mask:0xf
	v_sub_f32_e32 v3, v0, v1
	v_mov_b32_e32 v2, v1
	v_mov_b32_e32 v5, v3
	s_nop 1
	v_max_f32_dpp v5, v5, v5 row_shr:1 row_mask:0xf bank_mask:0xf
	s_nop 1
	v_max_f32_dpp v5, v5, v5 row_shr:2 row_mask:0xf bank_mask:0xf
	s_nop 1
	v_max_f32_dpp v5, v5, v5 row_shr:4 row_mask:0xf bank_mask:0xf
	s_nop 1
	v_max_f32_dpp v5, v5, v5 row_shr:8 row_mask:0xf bank_mask:0xf
	s_nop 1
	v_max_f32_dpp v5, v5, v5 row_bcast:15 row_mask:0xa bank_mask:0xf
	s_nop 1
	v_max_f32_dpp v5, v5, v5 row_bcast:31 row_mask:0xc bank_mask:0xf
	s_nop 0
	v_readlane_b32 s1, v5, 63
	v_readlane_b32 s30, v2, 63
	v_cmp_eq_u32_e32 vcc, 0, v19
	s_mov_b32 s0, 0x3fb8aa3b
	s_nop 0
	v_mov_b32_e32 v0, s30
	v_mov_b32_e32 v1, s1
	v_sub_f32_e32 v2, v3, v1
	v_mul_f32_e32 v3, 0x3fb8aa3b, v2
	v_fma_f32 v4, v2, s0, -v3
	v_rndne_f32_e32 v5, v3
	v_fmac_f32_e32 v4, 0x32a5705f, v2
	v_sub_f32_e32 v3, v3, v5
	v_add_f32_e32 v3, v3, v4
	v_exp_f32_e32 v3, v3
	v_cvt_i32_f32_e32 v4, v5
	s_mov_b32 s0, 0xc2ce8ed0
	v_cmp_ngt_f32_e64 s[0:1], s0, v2
	v_ldexp_f32 v3, v3, v4
	s_nop 0
	v_cndmask_b32_e64 v3, 0, v3, s[0:1]
	s_mov_b32 s0, 0x42b17218
	v_cmp_nlt_f32_e64 s[0:1], s0, v2
	s_nop 1
	v_cndmask_b32_e64 v2, v33, v3, s[0:1]
	v_lshl_add_u32 v3, v19, 2, s32
	ds_write_b32 v3, v2 offset:40960
	s_and_saveexec_b64 s[0:1], vcc
	s_cbranch_execz .Lmg_skipst
	s_lshl_b64 s[30:31], s[10:11], 4
	s_add_u32 s30, s21, s30
	s_addc_u32 s31, s22, s31
	s_waitcnt lgkmcnt(1)
	v_add_f32_e32 v1, v1, v0
	global_store_dwordx2 v17, v[0:1], s[30:31]

; DI void conv_unit(const u16* __restrict__ PM, const float* __restrict__ conv_w, const float* __restrict__ conv_b, int b, int sl0, int ch, float scale, float* a8) {
;   { const float4 b0 = *(const float4*)(conv_b + ch), b1 = *(const float4*)(conv_b + ch + 4); a8[0] = b0.x; a8[1] = b0.y; a8[2] = b0.z; a8[3] = b0.w; a8[4] = b1.x; a8[5] = b1.y; a8[6] = b1.z; a8[7] = b1.w; }
; #pragma unroll
;   for (int j = 0; j < 4; ++j) {
;     const int sl = sl0 - 3 + j;
;     if (sl >= 0) {
;       const uint4 raw = *(const uint4*)(PM + ((size_t)b * SEQ + sl) * 1024 + ch);
;       float x8[8]; unpack8(raw, x8);
;       const float4 w0 = *(const float4*)(conv_w + j * 1024 + ch), w1 = *(const float4*)(conv_w + j * 1024 + ch + 4);
;       a8[0] += w0.x * x8[0]; a8[1] += w0.y * x8[1]; a8[2] += w0.z * x8[2]; a8[3] += w0.w * x8[3];
;       a8[4] += w1.x * x8[4]; a8[5] += w1.y * x8[5]; a8[6] += w1.z * x8[6]; a8[7] += w1.w * x8[7];
;     }
;   }
; DI void mlstmA_item(const Params& p, char* lds, int item) {
;     ...
;   for (int i = 0; i < 2; ++i) {
;     const int q = tid + 512 * i, e = q >> 3, s8 = (q & 7) * 8;
;     *(uint4*)(VTs + e * 72 + s8) = *(const uint4*)(VTm + ((size_t)(bh * 128 + e)) * SEQ + c * 64 + s8);
;   }
;   __syncthreads();
.Lmg_next:
	s_add_i32 s80, s80, 1
	s_cmp_lt_u32 s80, 2
	s_cbranch_scc1 .Lmg_round
	s_mov_b32 s10, s94
	s_mov_b32 s96, 0
	s_branch .LBB0_324
.LBB0_323:
	s_or_b64 exec, exec, s[0:1]
	s_add_i32 s10, s10, s70
	s_add_i32 s96, s96, 0x100
	s_cmpk_gt_i32 s10, 0xfff
	s_barrier
	s_cbranch_scc1 .LBB0_342
.LBB0_324:
	v_and_b32_e32 v70, 15, v222
	s_bfe_u32 s72, s10, 0x20007
	v_lshlrev_b32_e32 v70, 3, v70
	s_lshl_b32 s72, s72, 7
	v_add_u32_e32 v70, s72, v70
	v_lshlrev_b32_e32 v71, 2, v70
	v_add_u32_e32 v72, 0x1000, v71
	v_add_u32_e32 v73, 0x2000, v71
	v_add_u32_e32 v74, 0x3000, v71
	global_load_dwordx4 v[140:143], v71, s[62:63] offset:2048
	global_load_dwordx4 v[144:147], v71, s[62:63] offset:2064
	global_load_dwordx4 v[148:151], v72, s[62:63] offset:2048
	global_load_dwordx4 v[152:155], v72, s[62:63] offset:2064
	global_load_dwordx4 v[156:159], v73, s[62:63] offset:2048
	global_load_dwordx4 v[160:163], v73, s[62:63] offset:2064
	global_load_dwordx4 v[164:167], v74, s[62:63] offset:2048
	global_load_dwordx4 v[168:171], v74, s[62:63] offset:2064
	global_load_dwordx4 v[224:227], v71, s[64:65] offset:2048
	global_load_dwordx4 v[228:231], v71, s[64:65] offset:2064
	s_ashr_i32 s74, s10, 9
	s_ashr_i32 s75, s74, 31
	s_lshl_b64 s[74:75], s[74:75], 24
	s_add_u32 s74, s74, s4
	s_addc_u32 s75, s75, s5
	v_lshlrev_b32_e32 v76, 1, v70
	v_mov_b32_e32 v77, 0
	v_lshl_add_u64 v[78:79], s[74:75], 0, v[76:77]
	s_and_b32 s76, s10, 0x7f
	s_lshl_b32 s76, s76, 6
	v_lshrrev_b32_e32 v75, 4, v222
	s_movk_i32 s77, 0x800
	v_add_u32_e32 v184, s76, v75
	v_add_u32_e32 v185, -1, v184
	v_mov_b32_e32 v114, 0
	v_mov_b32_e32 v115, 0
	v_mov_b32_e32 v116, 0
	v_mov_b32_e32 v117, 0
	v_mov_b32_e32 v118, 0
	v_mov_b32_e32 v119, 0
	v_mov_b32_e32 v120, 0
	v_mov_b32_e32 v121, 0
	v_mov_b32_e32 v122, 0
	v_mov_b32_e32 v123, 0
	v_mov_b32_e32 v124, 0
	v_mov_b32_e32 v125, 0
	v_mad_i64_i32 v[186:187], s[88:89], v185, s77, v[78:79]
	v_cmp_lt_i32_e64 s[84:85], 2, v184
	s_and_saveexec_b64 s[86:87], s[84:85]
	global_load_dwordx4 v[114:117], v[186:187], off offset:-3072
	s_or_b64 exec, exec, s[86:87]
	v_cmp_lt_i32_e64 s[84:85], 1, v184
	s_and_saveexec_b64 s[86:87], s[84:85]
	global_load_dwordx4 v[118:121], v[186:187], off offset:-1024
	s_or_b64 exec, exec, s[86:87]
	v_cmp_lt_i32_e64 s[84:85], 0, v184
	s_and_saveexec_b64 s[86:87], s[84:85]
	global_load_dwordx4 v[122:125], v[186:187], off offset:1024
	s_or_b64 exec, exec, s[86:87]
	global_load_dwordx4 v[126:129], v[186:187], off offset:3072
	v_add_u32_e32 v184, 32, v184
	v_add_u32_e32 v185, -1, v184
	v_mov_b32_e32 v130, 0
	v_mov_b32_e32 v131, 0
	v_mov_b32_e32 v132, 0
	v_mov_b32_e32 v133, 0
	v_mov_b32_e32 v134, 0
	v_mov_b32_e32 v135, 0
	v_mov_b32_e32 v136, 0
	v_mov_b32_e32 v137, 0
	v_mov_b32_e32 v172, 0
	v_mov_b32_e32 v173, 0
	v_mov_b32_e32 v174, 0
	v_mov_b32_e32 v175, 0
	v_mad_i64_i32 v[186:187], s[88:89], v185, s77, v[78:79]
	v_cmp_lt_i32_e64 s[84:85], 2, v184
	s_and_saveexec_b64 s[86:87], s[84:85]
	global_load_dwordx4 v[130:133], v[186:187], off offset:-3072
	s_or_b64 exec, exec, s[86:87]
	v_cmp_lt_i32_e64 s[84:85], 1, v184
	s_and_saveexec_b64 s[86:87], s[84:85]
	global_load_dwordx4 v[134:137], v[186:187], off offset:-1024
	s_or_b64 exec, exec, s[86:87]
	v_cmp_lt_i32_e64 s[84:85], 0, v184
	s_and_saveexec_b64 s[86:87], s[84:85]
	global_load_dwordx4 v[172:175], v[186:187], off offset:1024
	s_or_b64 exec, exec, s[86:87]
	global_load_dwordx4 v[176:179], v[186:187], off offset:3072
	v_mov_b32_e32 v18, v222
	s_and_b32 s18, s10, 0x7f
	s_ashr_i32 s12, s10, 9
	s_nop 0
	v_cmp_lt_u32_e32 vcc, 63, v18
	s_and_saveexec_b64 s[0:1], vcc
	s_xor_b64 s[0:1], exec, s[0:1]
	s_lshl_b32 s8, s18, 6
	s_ashr_i32 s13, s12, 31
	s_or_saveexec_b64 s[14:15], s[0:1]
	s_bfe_u32 s27, s10, 0x20007
	v_and_b32_e32 v19, 63, v18
	s_ashr_i32 s11, s10, 31
	v_mov_b64_e32 v[10:11], s[12:13]
	v_mov_b64_e32 v[0:1], s[8:9]
	v_mov_b32_e32 v50, s8
.LBB0_330:
	s_or_b64 exec, exec, s[14:15]
	v_add_u32_e32 v4, 0x200, v18
	s_and_b32 s0, s10, 0xffffff80
	v_lshlrev_b32_e32 v2, 4, v18
	v_ashrrev_i32_e32 v9, 3, v18
	v_ashrrev_i32_e32 v14, 3, v4
	v_and_b32_e32 v16, 0x70, v2
	v_add_u32_e32 v2, s0, v9
	v_add_u32_e32 v4, s0, v14
	v_lshl_add_u64 v[0:1], v[0:1], 1, s[6:7]
	v_ashrrev_i32_e32 v3, 31, v2
	v_ashrrev_i32_e32 v5, 31, v4
	v_lshl_add_u64 v[0:1], v[0:1], 0, v[16:17]
	v_lshlrev_b64 v[2:3], 14, v[2:3]
	v_lshlrev_b64 v[4:5], 14, v[4:5]
	v_lshl_add_u64 v[2:3], v[0:1], 0, v[2:3]
	v_lshl_add_u64 v[4:5], v[0:1], 0, v[4:5]
	global_load_dwordx4 v[0:3], v[2:3], off
	s_nop 0
	global_load_dwordx4 v[4:7], v[4:5], off
	v_lshlrev_b32_e32 v8, 3, v18
	v_and_b32_e32 v22, 0x78, v8
	v_add_u32_e32 v8, 0, v16
	v_lshl_or_b32 v15, s27, 7, v22
	v_mad_u64_u32 v[12:13], s[0:1], v9, s26, v[8:9]
	v_lshlrev_b32_e32 v16, 2, v15
	v_mad_u64_u32 v[8:9], s[0:1], v14, s26, v[8:9]
	v_lshlrev_b64 v[10:11], 24, v[10:11]
	v_lshl_add_u64 v[10:11], s[4:5], 0, v[10:11]
	v_mov_b32_e32 v13, v17
	s_mov_b64 s[0:1], 0x1800
	v_ashrrev_i32_e32 v51, 4, v18
	v_mad_u32_u24 v52, v22, s26, 0
	s_mov_b32 s8, 0
	s_waitcnt vmcnt(1)
	ds_write_b128 v12, v[0:3] offset:18432
	s_waitcnt vmcnt(0)
	ds_write_b128 v8, v[4:7] offset:18432
	s_waitcnt lgkmcnt(0)
	s_barrier
; DI u16 f2bf(float x) { return (u16)(pack2(x, 0.f) & 0xffffu); }
; DI void conv_unit(const u16* __restrict__ PM, const float* __restrict__ conv_w, const float* __restrict__ conv_b, int b, int sl0, int ch, float scale, float* a8) {
;   { const float4 b0 = *(const float4*)(conv_b + ch), b1 = *(const float4*)(conv_b + ch + 4); a8[0] = b0.x; a8[1] = b0.y; a8[2] = b0.z; a8[3] = b0.w; a8[4] = b1.x; a8[5] = b1.y; a8[6] = b1.z; a8[7] = b1.w; }
; #pragma unroll
;   for (int j = 0; j < 4; ++j) {
;     const int sl = sl0 - 3 + j;
;     if (sl >= 0) {
;       const uint4 raw = *(const uint4*)(PM + ((size_t)b * SEQ + sl) * 1024 + ch);
;       float x8[8]; unpack8(raw, x8);
;       const float4 w0 = *(const float4*)(conv_w + j * 1024 + ch), w1 = *(const float4*)(conv_w + j * 1024 + ch + 4);
;       a8[0] += w0.x * x8[0]; a8[1] += w0.y * x8[1]; a8[2] += w0.z * x8[2]; a8[3] += w0.w * x8[3];
;       a8[4] += w1.x * x8[4]; a8[5] += w1.y * x8[5]; a8[6] += w1.z * x8[6]; a8[7] += w1.w * x8[7];
;     }
;   }
; #pragma unroll
;   for (int e = 0; e < 8; ++e) { const float v = a8[e]; a8[e] = scale * v * __builtin_amdgcn_rcpf(1.f + __expf(-v)); }
; }
; DI void mlstmA_item(const Params& p, char* lds, int item) {
;     ...
; #pragma unroll 1
;   for (int i = 0; i < 2; ++i) {
;     const int cgk = tid & 15, t = (tid >> 4) + 32 * i;
;     float a8[8];
;     conv_unit(PM, p.in[5], p.in[6], b, c * 64 + t, 512 + hd * 128 + cgk * 8, 0.08838834764831845f, a8);
;     const float w = win[t];
; #pragma unroll
;     for (int e = 0; e < 8; ++e) KTs[(cgk * 8 + e) * 72 + t] = f2bf(a8[e] * w);
	s_waitcnt vmcnt(0)
	v_mov_b32_e32 v197, v51
	v_lshl_add_u32 v196, v197, 2, s96
	ds_read_b32 v196, v196 offset:40960
	v_lshl_add_u32 v198, v197, 1, v52
	v_lshlrev_b32_e32 v188, 16, v114
	v_and_b32_e32 v189, 0xffff0000, v114
	v_lshlrev_b32_e32 v190, 16, v115
	v_and_b32_e32 v191, 0xffff0000, v115
	v_lshlrev_b32_e32 v192, 16, v116
	v_and_b32_e32 v193, 0xffff0000, v116
	v_lshlrev_b32_e32 v194, 16, v117
	v_and_b32_e32 v195, 0xffff0000, v117
	v_pk_fma_f32 v[204:205], v[140:141], v[188:189], v[224:225]
	v_pk_fma_f32 v[206:207], v[142:143], v[190:191], v[226:227]
	v_pk_fma_f32 v[208:209], v[144:145], v[192:193], v[228:229]
	v_pk_fma_f32 v[210:211], v[146:147], v[194:195], v[230:231]
	v_lshlrev_b32_e32 v188, 16, v118
	v_and_b32_e32 v189, 0xffff0000, v118
	v_lshlrev_b32_e32 v190, 16, v119
	v_and_b32_e32 v191, 0xffff0000, v119
	v_lshlrev_b32_e32 v192, 16, v120
	v_and_b32_e32 v193, 0xffff0000, v120
	v_lshlrev_b32_e32 v194, 16, v121
	v_and_b32_e32 v195, 0xffff0000, v121
	v_pk_fma_f32 v[204:205], v[148:149], v[188:189], v[204:205]
	v_pk_fma_f32 v[206:207], v[150:151], v[190:191], v[206:207]
	v_pk_fma_f32 v[208:209], v[152:153], v[192:193], v[208:209]
	v_pk_fma_f32 v[210:211], v[154:155], v[194:195], v[210:211]
	v_lshlrev_b32_e32 v188, 16, v122
	v_and_b32_e32 v189, 0xffff0000, v122
	v_lshlrev_b32_e32 v190, 16, v123
	v_and_b32_e32 v191, 0xffff0000, v123
	v_lshlrev_b32_e32 v192, 16, v124
	v_and_b32_e32 v193, 0xffff0000, v124
	v_lshlrev_b32_e32 v194, 16, v125
	v_and_b32_e32 v195, 0xffff0000, v125
	v_pk_fma_f32 v[204:205], v[156:157], v[188:189], v[204:205]
	v_pk_fma_f32 v[206:207], v[158:159], v[190:191], v[206:207]
	v_pk_fma_f32 v[208:209], v[160:161], v[192:193], v[208:209]
	v_pk_fma_f32 v[210:211], v[162:163], v[194:195], v[210:211]
	v_lshlrev_b32_e32 v188, 16, v126
	v_and_b32_e32 v189, 0xffff0000, v126
	v_lshlrev_b32_e32 v190, 16, v127
	v_and_b32_e32 v191, 0xffff0000, v127
	v_lshlrev_b32_e32 v192, 16, v128
	v_and_b32_e32 v193, 0xffff0000, v128
	v_lshlrev_b32_e32 v194, 16, v129
	v_and_b32_e32 v195, 0xffff0000, v129
	v_pk_fma_f32 v[204:205], v[164:165], v[188:189], v[204:205]
	v_pk_fma_f32 v[206:207], v[166:167], v[190:191], v[206:207]
	v_pk_fma_f32 v[208:209], v[168:169], v[192:193], v[208:209]
	v_pk_fma_f32 v[210:211], v[170:171], v[194:195], v[210:211]
	v_mul_f32_e32 v212, 0xbfb8aa3b, v204
	v_mul_f32_e32 v213, 0xbfb8aa3b, v205
	v_mul_f32_e32 v214, 0xbfb8aa3b, v206
	v_mul_f32_e32 v215, 0xbfb8aa3b, v207
	v_mul_f32_e32 v216, 0xbfb8aa3b, v208
	v_mul_f32_e32 v217, 0xbfb8aa3b, v209
	v_mul_f32_e32 v218, 0xbfb8aa3b, v210
	v_mul_f32_e32 v219, 0xbfb8aa3b, v211
	v_mul_f32_e32 v188, 0x3db504f3, v204
	v_mul_f32_e32 v189, 0x3db504f3, v205
	v_mul_f32_e32 v190, 0x3db504f3, v206
	v_mul_f32_e32 v191, 0x3db504f3, v207
	v_mul_f32_e32 v192, 0x3db504f3, v208
	v_mul_f32_e32 v193, 0x3db504f3, v209
	v_mul_f32_e32 v194, 0x3db504f3, v210
	v_mul_f32_e32 v195, 0x3db504f3, v211
	v_exp_f32_e32 v212, v212
	v_exp_f32_e32 v213, v213
	v_exp_f32_e32 v214, v214
	v_exp_f32_e32 v215, v215
	v_exp_f32_e32 v216, v216
	v_exp_f32_e32 v217, v217
	v_exp_f32_e32 v218, v218
	v_exp_f32_e32 v219, v219
	v_add_f32_e32 v212, 1.0, v212
	v_add_f32_e32 v213, 1.0, v213
	v_add_f32_e32 v214, 1.0, v214
	v_add_f32_e32 v215, 1.0, v215
	v_add_f32_e32 v216, 1.0, v216
	v_add_f32_e32 v217, 1.0, v217
	v_add_f32_e32 v218, 1.0, v218
	v_add_f32_e32 v219, 1.0, v219
	v_rcp_f32_e32 v212, v212
	v_rcp_f32_e32 v213, v213
	v_rcp_f32_e32 v214, v214
	v_rcp_f32_e32 v215, v215
	v_rcp_f32_e32 v216, v216
	v_rcp_f32_e32 v217, v217
	v_rcp_f32_e32 v218, v218
	v_rcp_f32_e32 v219, v219
	v_mul_f32_e32 v188, v188, v212
	v_mul_f32_e32 v189, v189, v213
	v_mul_f32_e32 v190, v190, v214
	v_mul_f32_e32 v191, v191, v215
	v_mul_f32_e32 v192, v192, v216
	v_mul_f32_e32 v193, v193, v217
	v_mul_f32_e32 v194, v194, v218
	v_mul_f32_e32 v195, v195, v219
	s_waitcnt lgkmcnt(0)
; DI u16 f2bf(float x) { return (u16)(pack2(x, 0.f) & 0xffffu); }
; DI void conv_unit(const u16* __restrict__ PM, const float* __restrict__ conv_w, const float* __restrict__ conv_b, int b, int sl0, int ch, float scale, float* a8) {
;   { const float4 b0 = *(const float4*)(conv_b + ch), b1 = *(const float4*)(conv_b + ch + 4); a8[0] = b0.x; a8[1] = b0.y; a8[2] = b0.z; a8[3] = b0.w; a8[4] = b1.x; a8[5] = b1.y; a8[6] = b1.z; a8[7] = b1.w; }
; #pragma unroll
;   for (int j = 0; j < 4; ++j) {
;     const int sl = sl0 - 3 + j;
;     if (sl >= 0) {
;       const uint4 raw = *(const uint4*)(PM + ((size_t)b * SEQ + sl) * 1024 + ch);
;       float x8[8]; unpack8(raw, x8);
;       const float4 w0 = *(const float4*)(conv_w + j * 1024 + ch), w1 = *(const float4*)(conv_w + j * 1024 + ch + 4);
;       a8[0] += w0.x * x8[0]; a8[1] += w0.y * x8[1]; a8[2] += w0.z * x8[2]; a8[3] += w0.w * x8[3];
;       a8[4] += w1.x * x8[4]; a8[5] += w1.y * x8[5]; a8[6] += w1.z * x8[6]; a8[7] += w1.w * x8[7];
;     }
;   }
; #pragma unroll
;   for (int e = 0; e < 8; ++e) { const float v = a8[e]; a8[e] = scale * v * __builtin_amdgcn_rcpf(1.f + __expf(-v)); }
; }
; DI void mlstmA_item(const Params& p, char* lds, int item) {
;     ...
; #pragma unroll 1
;   for (int i = 0; i < 2; ++i) {
;     const int cgk = tid & 15, t = (tid >> 4) + 32 * i;
;     float a8[8];
;     conv_unit(PM, p.in[5], p.in[6], b, c * 64 + t, 512 + hd * 128 + cgk * 8, 0.08838834764831845f, a8);
;     const float w = win[t];
; #pragma unroll
;     for (int e = 0; e < 8; ++e) KTs[(cgk * 8 + e) * 72 + t] = f2bf(a8[e] * w);
	v_mul_f32_e32 v188, v196, v188
	v_mul_f32_e32 v189, v196, v189
	v_mul_f32_e32 v190, v196, v190
	v_mul_f32_e32 v191, v196, v191
	v_mul_f32_e32 v192, v196, v192
	v_mul_f32_e32 v193, v196, v193
	v_mul_f32_e32 v194, v196, v194
	v_mul_f32_e32 v195, v196, v195
	v_cvt_pk_bf16_f32 v188, v188, s77
	v_cvt_pk_bf16_f32 v189, v189, s77
	v_cvt_pk_bf16_f32 v190, v190, s77
	v_cvt_pk_bf16_f32 v191, v191, s77
	v_cvt_pk_bf16_f32 v192, v192, s77
	v_cvt_pk_bf16_f32 v193, v193, s77
	v_cvt_pk_bf16_f32 v194, v194, s77
	v_cvt_pk_bf16_f32 v195, v195, s77
	ds_write_b16 v198, v188
	ds_write_b16 v198, v189 offset:144
	ds_write_b16 v198, v190 offset:288
	ds_write_b16 v198, v191 offset:432
	ds_write_b16 v198, v192 offset:576
	ds_write_b16 v198, v193 offset:720
	ds_write_b16 v198, v194 offset:864
	ds_write_b16 v198, v195 offset:1008
	v_add_u32_e32 v197, 32, v51
	v_lshl_add_u32 v196, v197, 2, s96
	ds_read_b32 v196, v196 offset:40960
	v_lshl_add_u32 v198, v197, 1, v52
	v_lshlrev_b32_e32 v188, 16, v130
	v_and_b32_e32 v189, 0xffff0000, v130
	v_lshlrev_b32_e32 v190, 16, v131
	v_and_b32_e32 v191, 0xffff0000, v131
	v_lshlrev_b32_e32 v192, 16, v132
	v_and_b32_e32 v193, 0xffff0000, v132
	v_lshlrev_b32_e32 v194, 16, v133
	v_and_b32_e32 v195, 0xffff0000, v133
	v_pk_fma_f32 v[204:205], v[140:141], v[188:189], v[224:225]
	v_pk_fma_f32 v[206:207], v[142:143], v[190:191], v[226:227]
	v_pk_fma_f32 v[208:209], v[144:145], v[192:193], v[228:229]
	v_pk_fma_f32 v[210:211], v[146:147], v[194:195], v[230:231]
	v_lshlrev_b32_e32 v188, 16, v134
	v_and_b32_e32 v189, 0xffff0000, v134
	v_lshlrev_b32_e32 v190, 16, v135
	v_and_b32_e32 v191, 0xffff0000, v135
	v_lshlrev_b32_e32 v192, 16, v136
	v_and_b32_e32 v193, 0xffff0000, v136
	v_lshlrev_b32_e32 v194, 16, v137
	v_and_b32_e32 v195, 0xffff0000, v137
	v_pk_fma_f32 v[204:205], v[148:149], v[188:189], v[204:205]
	v_pk_fma_f32 v[206:207], v[150:151], v[190:191], v[206:207]
	v_pk_fma_f32 v[208:209], v[152:153], v[192:193], v[208:209]
	v_pk_fma_f32 v[210:211], v[154:155], v[194:195], v[210:211]
	v_lshlrev_b32_e32 v188, 16, v172
	v_and_b32_e32 v189, 0xffff0000, v172
	v_lshlrev_b32_e32 v190, 16, v173
	v_and_b32_e32 v191, 0xffff0000, v173
	v_lshlrev_b32_e32 v192, 16, v174
	v_and_b32_e32 v193, 0xffff0000, v174
	v_lshlrev_b32_e32 v194, 16, v175
	v_and_b32_e32 v195, 0xffff0000, v175
	v_pk_fma_f32 v[204:205], v[156:157], v[188:189], v[204:205]
	v_pk_fma_f32 v[206:207], v[158:159], v[190:191], v[206:207]
	v_pk_fma_f32 v[208:209], v[160:161], v[192:193], v[208:209]
	v_pk_fma_f32 v[210:211], v[162:163], v[194:195], v[210:211]
	v_lshlrev_b32_e32 v188, 16, v176
	v_and_b32_e32 v189, 0xffff0000, v176
	v_lshlrev_b32_e32 v190, 16, v177
	v_and_b32_e32 v191, 0xffff0000, v177
	v_lshlrev_b32_e32 v192, 16, v178
	v_and_b32_e32 v193, 0xffff0000, v178
	v_lshlrev_b32_e32 v194, 16, v179
	v_and_b32_e32 v195, 0xffff0000, v179
	v_pk_fma_f32 v[204:205], v[164:165], v[188:189], v[204:205]
	v_pk_fma_f32 v[206:207], v[166:167], v[190:191], v[206:207]
	v_pk_fma_f32 v[208:209], v[168:169], v[192:193], v[208:209]
	v_pk_fma_f32 v[210:211], v[170:171], v[194:195], v[210:211]
	v_mul_f32_e32 v212, 0xbfb8aa3b, v204
	v_mul_f32_e32 v213, 0xbfb8aa3b, v205
	v_mul_f32_e32 v214, 0xbfb8aa3b, v206
	v_mul_f32_e32 v215, 0xbfb8aa3b, v207
	v_mul_f32_e32 v216, 0xbfb8aa3b, v208
	v_mul_f32_e32 v217, 0xbfb8aa3b, v209
	v_mul_f32_e32 v218, 0xbfb8aa3b, v210
	v_mul_f32_e32 v219, 0xbfb8aa3b, v211
	v_mul_f32_e32 v188, 0x3db504f3, v204
	v_mul_f32_e32 v189, 0x3db504f3, v205
	v_mul_f32_e32 v190, 0x3db504f3, v206
	v_mul_f32_e32 v191, 0x3db504f3, v207
	v_mul_f32_e32 v192, 0x3db504f3, v208
	v_mul_f32_e32 v193, 0x3db504f3, v209
	v_mul_f32_e32 v194, 0x3db504f3, v210
	v_mul_f32_e32 v195, 0x3db504f3, v211
	v_exp_f32_e32 v212, v212
	v_exp_f32_e32 v213, v213
	v_exp_f32_e32 v214, v214
	v_exp_f32_e32 v215, v215
	v_exp_f32_e32 v216, v216
	v_exp_f32_e32 v217, v217
	v_exp_f32_e32 v218, v218
	v_exp_f32_e32 v219, v219
	v_add_f32_e32 v212, 1.0, v212
	v_add_f32_e32 v213, 1.0, v213
	v_add_f32_e32 v214, 1.0, v214
	v_add_f32_e32 v215, 1.0, v215
	v_add_f32_e32 v216, 1.0, v216
	v_add_f32_e32 v217, 1.0, v217
	v_add_f32_e32 v218, 1.0, v218
	v_add_f32_e32 v219, 1.0, v219
	v_rcp_f32_e32 v212, v212
	v_rcp_f32_e32 v213, v213
	v_rcp_f32_e32 v214, v214
	v_rcp_f32_e32 v215, v215
	v_rcp_f32_e32 v216, v216
	v_rcp_f32_e32 v217, v217
	v_rcp_f32_e32 v218, v218
	v_rcp_f32_e32 v219, v219
	v_mul_f32_e32 v188, v188, v212
	v_mul_f32_e32 v189, v189, v213
	v_mul_f32_e32 v190, v190, v214
	v_mul_f32_e32 v191, v191, v215
	v_mul_f32_e32 v192, v192, v216
	v_mul_f32_e32 v193, v193, v217
	v_mul_f32_e32 v194, v194, v218
	v_mul_f32_e32 v195, v195, v219
	s_waitcnt lgkmcnt(0)
	v_mul_f32_e32 v188, v196, v188
	v_mul_f32_e32 v189, v196, v189
	v_mul_f32_e32 v190, v196, v190
	v_mul_f32_e32 v191, v196, v191
	v_mul_f32_e32 v192, v196, v192
	v_mul_f32_e32 v193, v196, v193
	v_mul_f32_e32 v194, v196, v194
	v_mul_f32_e32 v195, v196, v195
	v_cvt_pk_bf16_f32 v188, v188, s77
	v_cvt_pk_bf16_f32 v189, v189, s77
	v_cvt_pk_bf16_f32 v190, v190, s77
	v_cvt_pk_bf16_f32 v191, v191, s77
	v_cvt_pk_bf16_f32 v192, v192, s77
	v_cvt_pk_bf16_f32 v193, v193, s77
	v_cvt_pk_bf16_f32 v194, v194, s77
	v_cvt_pk_bf16_f32 v195, v195, s77
	ds_write_b16 v198, v188
	ds_write_b16 v198, v189 offset:144
	ds_write_b16 v198, v190 offset:288
	ds_write_b16 v198, v191 offset:432
	ds_write_b16 v198, v192 offset:576
	ds_write_b16 v198, v193 offset:720
	ds_write_b16 v198, v194 offset:864
	ds_write_b16 v198, v195 offset:1008
